# v8 + full-128B-line LDS-DMA tile layout (8 rows x 128 B per DMA, XOR-swizzled reads) in QKV and FFN-up GEMM instances
# baseline (speedup 1.0000x reference)
; #define PG8_STAGE(bufoff, gbase, voff) do { _Pragma("unroll") for (int _i = 0; _i < 2; ++_i) \
;         __builtin_amdgcn_global_load_lds((const unsigned*)((const char*)(gbase) + (voff)[_i]), (LAS unsigned*)(lds + (bufoff) + ldsw + _i * 8192), 16, 0, 0); } while (0)
; #define PG8_BAR __builtin_amdgcn_s_barrier()
; template <class Epi, class Sched>
; __device__ __forceinline__ void gemm_phase(LAS unsigned char* lds, const GemmP g, const Sched& S, const Epi& E, int tid) {
;     ...
;     unsigned voffA[2], voffB[2];
; #pragma unroll
;     for (int i = 0; i < 2; ++i) { int R, C; stage_rc(tid * 16 + i * 8192, R, C); const int Rb = (R & ~31) + perm32(R & 31);
;         voffA[i] = (unsigned)(R * g.lda + C) * 2u; voffB[i] = (unsigned)(Rb * g.ldb + C) * 2u; }
;     ...
;     PG8_STAGE(PG8_SB(0, 0), cB, voffB); PG8_STAGE(PG8_SB(0, 1), cB + hstepB, voffB); PG8_STAGE(PG8_SA(0, 0), cA, voffA); PG8_STAGE(PG8_SA(0, 1), cA + hstepA, voffA);
;     if (wr == 1) PG8_BAR;
.LBB0_158:
	v_ashrrev_i32_e32 v2, 31, v0
	v_lshrrev_b32_e32 v2, 26, v2
	v_lshlrev_b32_e32 v1, 4, v0
	v_add_u32_e32 v2, v0, v2
	v_bfe_i32 v0, v0, 27, 1
	v_lshrrev_b32_e32 v0, 22, v0
	v_add_u32_e32 v0, v1, v0
	v_and_b32_e32 v0, 0xfffffc00, v0
	v_sub_u32_e32 v0, v1, v0
	v_ashrrev_i32_e32 v9, 6, v2
	v_lshrrev_b32_e32 v2, 4, v0
	v_bitop3_b32 v2, v2, v0, 32 bitop3:0x6c
	v_ashrrev_i32_e32 v0, 31, v0
	v_lshrrev_b32_e32 v0, 26, v0
	v_add_u32_e32 v0, v2, v0
	v_lshlrev_b32_e32 v3, 3, v9
	v_ashrrev_i32_e32 v10, 6, v0
	v_and_b32_e32 v0, 0xc0, v0
	v_and_b32_e32 v3, -16, v3
	v_sub_u32_e32 v0, v2, v0
	v_mov_b32_e32 v2, 1
	v_add_u32_e32 v3, v10, v3
	v_ashrrev_i16_sdwa v0, v2, sext(v0) dst_sel:DWORD dst_unused:UNUSED_PAD src0_sel:DWORD src1_sel:BYTE_0
	v_lshlrev_b32_e32 v4, 5, v9
	v_bfe_i32 v11, v0, 0, 16
	v_lshlrev_b32_e32 v0, 1, v3
	v_lshrrev_b32_e32 v5, 2, v3
	v_and_b32_e32 v6, 3, v10
	s_mov_b32 s0, 0x1fffe0
	v_and_b32_e32 v4, 32, v4
	v_and_b32_e32 v0, 24, v0
	v_and_b32_e32 v5, 4, v5
	v_and_or_b32 v6, v3, s0, v6
	v_or3_b32 v0, v6, v5, v0
	v_add_lshl_u32 v4, v4, v11, 1
	v_lshl_add_u32 v130, v0, 11, v4
	v_add_u32_e32 v0, 0x2000, v1
	v_ashrrev_i32_e32 v1, 31, v0
	v_lshrrev_b32_e32 v1, 22, v1
	v_add_u32_e32 v1, v0, v1
	v_ashrrev_i32_e32 v12, 10, v1
	v_mul_i32_i24_e32 v1, 0x400, v12
	v_sub_u32_e32 v0, v0, v1
	v_lshrrev_b32_e32 v1, 4, v0
	v_bitop3_b32 v0, v1, v0, 32 bitop3:0x6c
	v_lshl_add_u32 v128, v3, 11, v4
	v_ashrrev_i32_e32 v3, 31, v0
	v_lshrrev_b32_e32 v3, 26, v3
	v_add_u32_e32 v3, v0, v3
	v_lshlrev_b32_e32 v1, 3, v12
	v_ashrrev_i32_e32 v13, 6, v3
	v_and_b32_e32 v3, 0xc0, v3
	v_and_b32_e32 v1, -16, v1
	v_sub_u32_e32 v0, v0, v3
	s_ashr_i32 s14, s6, 6
	v_add_u32_e32 v1, v13, v1
	v_ashrrev_i16_sdwa v0, v2, sext(v0) dst_sel:DWORD dst_unused:UNUSED_PAD src0_sel:DWORD src1_sel:BYTE_0
	s_lshl_b32 s52, s14, 10
	v_lshlrev_b32_e32 v4, 5, v12
	v_bfe_i32 v14, v0, 0, 16
	v_lshlrev_b32_e32 v0, 1, v1
	v_lshrrev_b32_e32 v2, 2, v1
	v_and_b32_e32 v3, 3, v13
	s_add_i32 s53, s52, 0
	v_and_b32_e32 v4, 32, v4
	v_and_b32_e32 v0, 24, v0
	v_and_b32_e32 v2, 4, v2
	v_and_or_b32 v3, v1, s0, v3
	s_add_i32 m0, s53, 0x10000
	s_ashr_i32 s7, s6, 8
	v_or3_b32 v0, v3, v2, v0
	v_add_lshl_u32 v2, v4, v14, 1
	v_lshrrev_b32_e32 v230, 3, v8
	v_lshrrev_b32_e32 v231, 4, v8
	v_and_b32_e32 v232, 7, v8
	v_xor_b32_e32 v232, v232, v231
	s_and_b32 s78, s14, 1
	s_lshl_b32 s79, s78, 2
	v_xor_b32_e32 v232, s79, v232
	v_lshlrev_b32_e32 v232, 4, v232
	s_lshl_b32 s80, s14, 3
	v_add_u32_e32 v233, s80, v230
	v_lshl_or_b32 v128, v233, 11, v232
	v_add_u32_e32 v132, 0x20000, v128
	s_lshr_b32 s80, s14, 2
	s_lshl_b32 s80, s80, 5
	s_lshl_b32 s81, s78, 4
	s_add_i32 s80, s80, s81
	s_bfe_u32 s81, s14, 0x10001
	s_lshl_b32 s81, s81, 2
	s_add_i32 s80, s80, s81
	v_lshrrev_b32_e32 v233, 5, v8
	v_and_b32_e32 v230, 3, v230
	v_lshl_or_b32 v233, v233, 3, v230
	v_add_u32_e32 v233, s80, v233
	v_lshl_or_b32 v130, v233, 11, v232
	v_add_u32_e32 v134, 0x20000, v130
	global_load_lds_dwordx4 v130, s[44:45]
	s_add_i32 m0, s53, 0x12000
	s_add_u32 s0, s44, 0x40000
	global_load_lds_dwordx4 v134, s[44:45]
	s_addc_u32 s1, s45, 0
	s_add_i32 m0, s53, 0x14000
	s_add_i32 s54, s53, 0x2000
	global_load_lds_dwordx4 v130, s[0:1]
	s_add_i32 m0, s53, 0x16000
	s_nop 0
	global_load_lds_dwordx4 v134, s[0:1]
	s_mov_b32 m0, s53
	s_add_u32 s0, s4, 0x40000
	global_load_lds_dwordx4 v128, s[4:5]
	s_mov_b32 m0, s54
	s_addc_u32 s1, s5, 0
	s_add_i32 s55, s53, 0x4000
	global_load_lds_dwordx4 v132, s[4:5]
	s_mov_b32 m0, s55
	s_add_i32 s56, s53, 0x6000
	global_load_lds_dwordx4 v128, s[0:1]
	s_mov_b32 m0, s56
	v_mov_b32_e32 v131, 0
	global_load_lds_dwordx4 v132, s[0:1]
	v_mov_b32_e32 v135, v131
	v_mov_b32_e32 v129, v131
	v_mov_b32_e32 v133, v131
	s_cmp_eq_u32 s7, 1
	s_mov_b32 s57, 0
	v_lshl_add_u64 v[6:7], s[44:45], 0, v[130:131]
	v_lshl_add_u64 v[4:5], s[44:45], 0, v[134:135]
	v_lshl_add_u64 v[0:1], s[4:5], 0, v[128:129]
	s_cselect_b64 s[0:1], -1, 0
	s_cmp_lg_u32 s7, 1
	v_lshl_add_u64 v[2:3], s[4:5], 0, v[132:133]
	s_cbranch_scc1 .LBB0_160
	s_barrier
; #define PG8_STAGE(bufoff, gbase, voff) do { _Pragma("unroll") for (int _i = 0; _i < 2; ++_i) \
;         __builtin_amdgcn_global_load_lds((const unsigned*)((const char*)(gbase) + (voff)[_i]), (LAS unsigned*)(lds + (bufoff) + ldsw + _i * 8192), 16, 0, 0); } while (0)
; #define PG8_WAIT_V(n) asm volatile("s_waitcnt vmcnt(" #n ")" ::: "memory")
; #define PG8_BAR __builtin_amdgcn_s_barrier()
; template <class Epi, class Sched>
; __device__ __forceinline__ void gemm_phase(LAS unsigned char* lds, const GemmP g, const Sched& S, const Epi& E, int tid) {
;     ...
;     const size_t kstep = (size_t)(BK * 2);
;     const size_t hstepA = (size_t)HALF * g.lda * 2, hstepB = (size_t)HALF * g.ldb * 2;
;     const unsigned ldsw = (unsigned)wid * 1024u;
;     const int aoff = lds_byte(wr * 64 + fr, fq * 8), boff = lds_byte(wc * 32 + fr, fq * 8);
;     ...
;     PG8_WAIT_V(2); PG8_BAR;
;     PG8_STAGE(PG8_SB(1, 0), cB + kstep, voffB); PG8_STAGE(PG8_SA(1, 0), cA + kstep, voffA); PG8_STAGE(PG8_SB(1, 1), cB + hstepB + kstep, voffB);
;     PG8_WAIT_V(6); PG8_BAR;
.LBB0_160:
	s_add_u32 s58, s10, 0x13000000
	s_addc_u32 s59, s11, 0
	s_add_u32 s12, s10, 0x35800000
	s_addc_u32 s13, s11, 0
	s_lshl_b32 s14, s14, 5
	s_and_b32 s61, s14, 0x60
	s_mov_b64 s[14:15], 0x80
	s_add_i32 m0, s53, 0x18000
	v_lshl_add_u64 v[6:7], v[6:7], 0, s[14:15]
	s_lshl_b32 s60, s7, 6
	s_lshl_b32 s7, s7, 13
	s_lshl_b32 s18, s61, 7
	s_waitcnt vmcnt(2)
	s_barrier
	global_load_lds_dwordx4 v[6:7], off
	v_lshl_add_u64 v[4:5], v[4:5], 0, s[14:15]
	s_add_i32 m0, s53, 0x1a000
	s_add_i32 s62, s53, 0x8000
	s_add_i32 s63, s53, 0xa000
	global_load_lds_dwordx4 v[4:5], off
	v_lshl_add_u64 v[0:1], v[0:1], 0, s[14:15]
	s_mov_b32 m0, s62
	s_add_u32 s16, s44, 0x40080
	global_load_lds_dwordx4 v[0:1], off
	v_lshl_add_u64 v[0:1], v[2:3], 0, s[14:15]
	s_mov_b32 m0, s63
	s_addc_u32 s17, s45, 0
	global_load_lds_dwordx4 v[0:1], off
	s_add_i32 m0, s53, 0x1c000
	v_lshl_add_u64 v[0:1], s[16:17], 0, v[130:131]
	global_load_lds_dwordx4 v[0:1], off
	v_lshl_add_u64 v[0:1], s[16:17], 0, v[134:135]
	s_add_i32 m0, s53, 0x1e000
	s_cmpk_lt_u32 s6, 0x100
	global_load_lds_dwordx4 v[0:1], off
	v_and_b32_e32 v0, 15, v8
	v_and_b32_e32 v1, 48, v8
	v_lshl_or_b32 v0, v0, 6, v1
	v_lshlrev_b32_e32 v1, 2, v8
	v_and_b32_e32 v1, 32, v1
	v_bitop3_b32 v2, v0, s7, v1 bitop3:0xde
	v_bitop3_b32 v156, s18, v0, v1 bitop3:0xf6
	v_lshlrev_b32_e32 v0, 14, v12
	v_and_b32_e32 v0, 0xffff8000, v0
	v_lshl_add_u32 v0, v13, 11, v0
	v_and_b32_e32 v1, 1, v12
	v_lshl_or_b32 v0, v1, 6, v0
	v_lshl_add_u32 v136, v14, 1, v0
	v_lshlrev_b32_e32 v0, 14, v9
	v_and_b32_e32 v0, 0xffff8000, v0
	s_waitcnt vmcnt(6)
	v_lshl_add_u32 v0, v10, 11, v0
	v_and_b32_e32 v1, 1, v9
	s_cselect_b64 s[16:17], -1, 0
	v_lshl_or_b32 v0, v1, 6, v0
	s_add_i32 s67, 0, 0x10000
	s_add_i32 s68, 0, 0x14000
	s_ashr_i32 s64, s43, 31
	s_ashr_i32 s65, s42, 31
	v_mov_b32_e32 v137, v131
	v_lshl_add_u32 v138, v11, 1, v0
	v_mov_b32_e32 v139, v131
	v_mov_b64_e32 v[140:141], 0xc60
	v_mov_b64_e32 v[142:143], 0xc5f
	s_movk_i32 s66, 0x18d
	v_add_u32_e32 v157, s67, v156
	v_add_u32_e32 v158, s68, v156
	v_add_u32_e32 v159, 0, v2
	s_mov_b32 s69, 0x20800000
	s_mov_b32 s70, 0x21000000
	v_mov_b32_e32 v160, 0x358637bd
	s_mov_b64 s[18:19], 0x4000
	s_mov_b64 s[20:21], 0x8000
	s_mov_b64 s[22:23], 0xc000
	s_mov_b64 s[24:25], 0x20000
	s_mov_b64 s[26:27], 0x24000
	s_mov_b64 s[28:29], 0x28000
	s_mov_b64 s[30:31], 0x2c000
	v_mov_b32_e32 v161, 0x3e38aa3b
	s_mov_b64 s[38:39], s[44:45]
	s_mov_b64 s[36:37], s[4:5]
	v_and_b32_e32 v230, 15, v8
	v_lshrrev_b32_e32 v231, 4, v8
	v_lshrrev_b32_e32 v232, 3, v230
	v_bfe_u32 v233, v230, 1, 2
	v_xor_b32_e32 v233, v233, v231
	v_lshl_or_b32 v233, v232, 2, v233
	v_lshlrev_b32_e32 v233, 4, v233
	v_and_b32_e32 v234, 7, v230
	v_lshl_or_b32 v233, v234, 7, v233
	v_lshl_or_b32 v233, v232, 10, v233
	s_lshr_b32 s78, s52, 12
	s_lshl_b32 s78, s78, 13
	s_bfe_u32 s79, s52, 0x2000a
	s_lshl_b32 s79, s79, 12
	v_add_u32_e32 v159, s78, v233
	v_add_u32_e32 v156, s79, v233
	v_xor_b32_e32 v226, 64, v159
	v_xor_b32_e32 v227, 64, v156
	v_add_u32_e32 v157, s67, v156
	v_add_u32_e32 v158, s68, v156
	v_add_u32_e32 v228, s67, v227
	v_add_u32_e32 v229, s68, v227
	v_mov_b32_e32 v136, v132
	v_mov_b32_e32 v138, v128
	s_barrier
	s_branch .LBB0_163

; #define PG8_STAGE(bufoff, gbase, voff) do { _Pragma("unroll") for (int _i = 0; _i < 2; ++_i) \
;         __builtin_amdgcn_global_load_lds((const unsigned*)((const char*)(gbase) + (voff)[_i]), (LAS unsigned*)(lds + (bufoff) + ldsw + _i * 8192), 16, 0, 0); } while (0)
; #define PG8_LDA(dst, b, h) do { _Pragma("unroll") for (int m = 0; m < 4; ++m) _Pragma("unroll") for (int k = 0; k < 2; ++k) dst[m][k] = *(const LAS bf16x8*)(lds + PG8_SA(b, h) + aoff + m * 2048 + k * 1024); } while (0)
; #define PG8_LDB(dst, b, h) do { _Pragma("unroll") for (int n = 0; n < 2; ++n) _Pragma("unroll") for (int k = 0; k < 2; ++k) dst[n][k] = *(const LAS bf16x8*)(lds + PG8_SB(b, h) + boff + n * 2048 + k * 1024); } while (0)
; #define PG8_MMA(ai, bj, At, Bt) do { __builtin_amdgcn_s_setprio(1); _Pragma("unroll") for (int m = 0; m < 4; ++m) _Pragma("unroll") for (int n = 0; n < 2; ++n) _Pragma("unroll") for (int k = 0; k < 2; ++k) \
;         acc[ai][bj][m][n] = __builtin_amdgcn_mfma_f32_16x16x32_bf16(Bt[n][k], At[m][k], acc[ai][bj][m][n], 0, 0, 0); __builtin_amdgcn_s_setprio(0); } while (0)
; #define PG8_WAIT_V(n) asm volatile("s_waitcnt vmcnt(" #n ")" ::: "memory")
; #define PG8_WAIT_L(n) asm volatile("s_waitcnt lgkmcnt(" #n ")" ::: "memory")
; #define PG8_BAR __builtin_amdgcn_s_barrier()
; #define PG8_SCHED __builtin_amdgcn_sched_barrier(0)
; template <class Epi, class Sched>
; __device__ __forceinline__ void gemm_phase(LAS unsigned char* lds, const GemmP g, const Sched& S, const Epi& E, int tid) {
;     ...
;             const bool last = (t == nt - 2);
;             const char* a1 = cA + (size_t)(t + 1) * kstep;
;             const char* a2 = last ? nA : cA + (size_t)(t + 2) * kstep; const char* b2 = last ? nB : cB + (size_t)(t + 2) * kstep;
;             const char* a3 = a2 + kstep; const char* b3 = b2 + kstep;
;             PG8_LDB(B0, 0, 0); PG8_LDB(B1, 0, 1); PG8_SCHED; PG8_LDA(At, 0, 0); PG8_STAGE(PG8_SA(1, 1), a1 + hstepA, voffA);
;             PG8_WAIT_V(8); PG8_WAIT_L(0); PG8_BAR; PG8_MMA(0, 0, At, B0); PG8_MMA(0, 1, At, B1); PG8_BAR; PG8_SCHED;
;             PG8_LDA(At, 0, 1); PG8_STAGE(PG8_SB(0, 0), b2, voffB); PG8_STAGE(PG8_SB(0, 1), b2 + hstepB, voffB); PG8_STAGE(PG8_SA(0, 0), a2, voffA);
.LBB0_166:
	ds_read_b128 v[144:147], v157
	ds_read_b128 v[148:151], v228
	ds_read_b128 v[152:155], v157 offset:2048
	ds_read_b128 v[162:165], v228 offset:2048
	ds_read_b128 v[166:169], v158
	ds_read_b128 v[170:173], v229
	ds_read_b128 v[174:177], v158 offset:2048
	ds_read_b128 v[178:181], v229 offset:2048
	s_add_u32 s44, s4, 0xfffc0080
	s_addc_u32 s45, s5, -1
	s_cmp_eq_u32 s73, 12
	s_cselect_b32 s47, s37, s45
	s_cselect_b32 s46, s36, s44
	s_cselect_b32 s45, s39, s72
	s_cselect_b32 s44, s38, s71
	v_lshl_add_u64 v[214:215], s[4:5], 0, v[138:139]
	s_add_i32 m0, s53, 0xc000
	ds_read_b128 v[182:185], v159
	ds_read_b128 v[186:189], v226
	ds_read_b128 v[190:193], v159 offset:2048
	ds_read_b128 v[194:197], v226 offset:2048
	ds_read_b128 v[198:201], v159 offset:4096
	ds_read_b128 v[202:205], v226 offset:4096
	ds_read_b128 v[206:209], v159 offset:6144
	ds_read_b128 v[210:213], v226 offset:6144
	global_load_lds_dwordx4 v[214:215], off
	v_lshl_add_u64 v[214:215], s[4:5], 0, v[136:137]
	s_add_i32 m0, s53, 0xe000
	s_nop 0
	global_load_lds_dwordx4 v[214:215], off
	s_cmp_eq_u32 s73, -2
	s_cbranch_scc1 .Lfirstit_1
	s_waitcnt vmcnt(8)
.Lfirstit_1:
	s_waitcnt lgkmcnt(0)
	s_barrier
	s_setprio 1
	s_waitcnt lgkmcnt(0)
	v_mfma_f32_16x16x32_bf16 v[124:127], v[144:147], v[182:185], v[124:127]
	v_mfma_f32_16x16x32_bf16 v[120:123], v[152:155], v[182:185], v[120:123]
	v_mfma_f32_16x16x32_bf16 v[108:111], v[144:147], v[190:193], v[108:111]
	v_mfma_f32_16x16x32_bf16 v[104:107], v[152:155], v[190:193], v[104:107]
	v_mfma_f32_16x16x32_bf16 v[92:95], v[144:147], v[198:201], v[92:95]
	v_mfma_f32_16x16x32_bf16 v[88:91], v[152:155], v[198:201], v[88:91]
	v_mfma_f32_16x16x32_bf16 v[76:79], v[144:147], v[206:209], v[76:79]
	v_mfma_f32_16x16x32_bf16 v[72:75], v[152:155], v[206:209], v[72:75]
	v_mfma_f32_16x16x32_bf16 v[124:127], v[148:151], v[186:189], v[124:127]
	v_mfma_f32_16x16x32_bf16 v[120:123], v[162:165], v[186:189], v[120:123]
	v_mfma_f32_16x16x32_bf16 v[108:111], v[148:151], v[194:197], v[108:111]
	v_mfma_f32_16x16x32_bf16 v[104:107], v[162:165], v[194:197], v[104:107]
	v_mfma_f32_16x16x32_bf16 v[92:95], v[148:151], v[202:205], v[92:95]
	v_mfma_f32_16x16x32_bf16 v[88:91], v[162:165], v[202:205], v[88:91]
	v_mfma_f32_16x16x32_bf16 v[76:79], v[148:151], v[210:213], v[76:79]
	v_mfma_f32_16x16x32_bf16 v[72:75], v[162:165], v[210:213], v[72:75]
	s_setprio 0
	s_setprio 1
	v_mfma_f32_16x16x32_bf16 v[116:119], v[166:169], v[182:185], v[116:119]
	v_mfma_f32_16x16x32_bf16 v[112:115], v[174:177], v[182:185], v[112:115]
	v_mfma_f32_16x16x32_bf16 v[100:103], v[166:169], v[190:193], v[100:103]
	v_mfma_f32_16x16x32_bf16 v[96:99], v[174:177], v[190:193], v[96:99]
	v_mfma_f32_16x16x32_bf16 v[84:87], v[166:169], v[198:201], v[84:87]
	v_mfma_f32_16x16x32_bf16 v[80:83], v[174:177], v[198:201], v[80:83]
	v_mfma_f32_16x16x32_bf16 v[68:71], v[166:169], v[206:209], v[68:71]
	v_mfma_f32_16x16x32_bf16 v[64:67], v[174:177], v[206:209], v[64:67]
	v_mfma_f32_16x16x32_bf16 v[116:119], v[170:173], v[186:189], v[116:119]
	v_mfma_f32_16x16x32_bf16 v[112:115], v[178:181], v[186:189], v[112:115]
	v_mfma_f32_16x16x32_bf16 v[100:103], v[170:173], v[194:197], v[100:103]
	v_mfma_f32_16x16x32_bf16 v[96:99], v[178:181], v[194:197], v[96:99]
	v_mfma_f32_16x16x32_bf16 v[84:87], v[170:173], v[202:205], v[84:87]
	v_mfma_f32_16x16x32_bf16 v[80:83], v[178:181], v[202:205], v[80:83]
	v_mfma_f32_16x16x32_bf16 v[68:71], v[170:173], v[210:213], v[68:71]
	v_mfma_f32_16x16x32_bf16 v[64:67], v[178:181], v[210:213], v[64:67]
	s_setprio 0
	s_barrier
	s_add_i32 s74, s67, s52
	v_lshl_add_u64 v[214:215], s[44:45], 0, v[130:131]
	s_mov_b32 m0, s74
	ds_read_b128 v[182:185], v159 offset:16384
	ds_read_b128 v[186:189], v226 offset:16384
	ds_read_b128 v[190:193], v159 offset:18432
	ds_read_b128 v[194:197], v226 offset:18432
	ds_read_b128 v[198:201], v159 offset:20480
	ds_read_b128 v[202:205], v226 offset:20480
	ds_read_b128 v[206:209], v159 offset:22528
	ds_read_b128 v[210:213], v226 offset:22528
	global_load_lds_dwordx4 v[214:215], off
	s_add_i32 m0, s74, 0x2000
	s_add_u32 s74, s44, 0x40000
	v_lshl_add_u64 v[216:217], s[44:45], 0, v[134:135]
	s_addc_u32 s75, s45, 0
	s_add_i32 s76, s68, s52
	global_load_lds_dwordx4 v[216:217], off
	v_lshl_add_u64 v[218:219], s[74:75], 0, v[130:131]
	s_mov_b32 m0, s76
	v_lshl_add_u64 v[220:221], s[46:47], 0, v[132:133]
	global_load_lds_dwordx4 v[218:219], off
	v_lshl_add_u64 v[218:219], s[74:75], 0, v[134:135]
	s_add_i32 m0, s76, 0x2000
	s_nop 0
	global_load_lds_dwordx4 v[218:219], off
	v_lshl_add_u64 v[218:219], s[46:47], 0, v[128:129]
	s_mov_b32 m0, s53
	s_nop 0
	global_load_lds_dwordx4 v[218:219], off
	s_mov_b32 m0, s54
	s_nop 0
	global_load_lds_dwordx4 v[220:221], off
	s_waitcnt vmcnt(8)
	s_waitcnt lgkmcnt(0)
	s_barrier
; #define PG8_STAGE(bufoff, gbase, voff) do { _Pragma("unroll") for (int _i = 0; _i < 2; ++_i) \
;         __builtin_amdgcn_global_load_lds((const unsigned*)((const char*)(gbase) + (voff)[_i]), (LAS unsigned*)(lds + (bufoff) + ldsw + _i * 8192), 16, 0, 0); } while (0)
; #define PG8_LDA(dst, b, h) do { _Pragma("unroll") for (int m = 0; m < 4; ++m) _Pragma("unroll") for (int k = 0; k < 2; ++k) dst[m][k] = *(const LAS bf16x8*)(lds + PG8_SA(b, h) + aoff + m * 2048 + k * 1024); } while (0)
; #define PG8_LDB(dst, b, h) do { _Pragma("unroll") for (int n = 0; n < 2; ++n) _Pragma("unroll") for (int k = 0; k < 2; ++k) dst[n][k] = *(const LAS bf16x8*)(lds + PG8_SB(b, h) + boff + n * 2048 + k * 1024); } while (0)
; #define PG8_MMA(ai, bj, At, Bt) do { __builtin_amdgcn_s_setprio(1); _Pragma("unroll") for (int m = 0; m < 4; ++m) _Pragma("unroll") for (int n = 0; n < 2; ++n) _Pragma("unroll") for (int k = 0; k < 2; ++k) \
;         acc[ai][bj][m][n] = __builtin_amdgcn_mfma_f32_16x16x32_bf16(Bt[n][k], At[m][k], acc[ai][bj][m][n], 0, 0, 0); __builtin_amdgcn_s_setprio(0); } while (0)
; #define PG8_WAIT_V(n) asm volatile("s_waitcnt vmcnt(" #n ")" ::: "memory")
; #define PG8_WAIT_L(n) asm volatile("s_waitcnt lgkmcnt(" #n ")" ::: "memory")
; #define PG8_BAR __builtin_amdgcn_s_barrier()
; #define PG8_SCHED __builtin_amdgcn_sched_barrier(0)
; template <class Epi, class Sched>
; __device__ __forceinline__ void gemm_phase(LAS unsigned char* lds, const GemmP g, const Sched& S, const Epi& E, int tid) {
;     ...
;             PG8_WAIT_V(8); PG8_WAIT_L(0); PG8_BAR; PG8_MMA(1, 0, At, B0); PG8_MMA(1, 1, At, B1); PG8_BAR; PG8_SCHED;
;             PG8_LDB(B0, 1, 0); PG8_LDB(B1, 1, 1); PG8_SCHED; PG8_LDA(At, 1, 0); PG8_STAGE(PG8_SA(0, 1), a2 + hstepA, voffA);
;             PG8_WAIT_V(8); PG8_WAIT_L(0); PG8_BAR; PG8_MMA(0, 0, At, B0); PG8_MMA(0, 1, At, B1); PG8_BAR; PG8_SCHED;
	s_setprio 1
	s_waitcnt lgkmcnt(0)
	v_mfma_f32_16x16x32_bf16 v[60:63], v[144:147], v[182:185], v[60:63]
	v_mfma_f32_16x16x32_bf16 v[56:59], v[152:155], v[182:185], v[56:59]
	v_mfma_f32_16x16x32_bf16 v[44:47], v[144:147], v[190:193], v[44:47]
	v_mfma_f32_16x16x32_bf16 v[40:43], v[152:155], v[190:193], v[40:43]
	v_mfma_f32_16x16x32_bf16 v[28:31], v[144:147], v[198:201], v[28:31]
	v_mfma_f32_16x16x32_bf16 v[24:27], v[152:155], v[198:201], v[24:27]
	v_mfma_f32_16x16x32_bf16 v[12:15], v[144:147], v[206:209], v[12:15]
	v_mfma_f32_16x16x32_bf16 v[8:11], v[152:155], v[206:209], v[8:11]
	v_mfma_f32_16x16x32_bf16 v[60:63], v[148:151], v[186:189], v[60:63]
	v_mfma_f32_16x16x32_bf16 v[56:59], v[162:165], v[186:189], v[56:59]
	v_mfma_f32_16x16x32_bf16 v[44:47], v[148:151], v[194:197], v[44:47]
	v_mfma_f32_16x16x32_bf16 v[40:43], v[162:165], v[194:197], v[40:43]
	v_mfma_f32_16x16x32_bf16 v[28:31], v[148:151], v[202:205], v[28:31]
	v_mfma_f32_16x16x32_bf16 v[24:27], v[162:165], v[202:205], v[24:27]
	v_mfma_f32_16x16x32_bf16 v[12:15], v[148:151], v[210:213], v[12:15]
	v_mfma_f32_16x16x32_bf16 v[8:11], v[162:165], v[210:213], v[8:11]
	s_setprio 0
	s_setprio 1
	v_mfma_f32_16x16x32_bf16 v[52:55], v[166:169], v[182:185], v[52:55]
	v_mfma_f32_16x16x32_bf16 v[48:51], v[174:177], v[182:185], v[48:51]
	v_mfma_f32_16x16x32_bf16 v[36:39], v[166:169], v[190:193], v[36:39]
	v_mfma_f32_16x16x32_bf16 v[32:35], v[174:177], v[190:193], v[32:35]
	v_mfma_f32_16x16x32_bf16 v[20:23], v[166:169], v[198:201], v[20:23]
	v_mfma_f32_16x16x32_bf16 v[16:19], v[174:177], v[198:201], v[16:19]
	v_mfma_f32_16x16x32_bf16 v[4:7], v[166:169], v[206:209], v[4:7]
	v_mfma_f32_16x16x32_bf16 v[0:3], v[174:177], v[206:209], v[0:3]
	v_mfma_f32_16x16x32_bf16 v[52:55], v[170:173], v[186:189], v[52:55]
	v_mfma_f32_16x16x32_bf16 v[48:51], v[178:181], v[186:189], v[48:51]
	v_mfma_f32_16x16x32_bf16 v[36:39], v[170:173], v[194:197], v[36:39]
	v_mfma_f32_16x16x32_bf16 v[32:35], v[178:181], v[194:197], v[32:35]
	v_mfma_f32_16x16x32_bf16 v[20:23], v[170:173], v[202:205], v[20:23]
	v_mfma_f32_16x16x32_bf16 v[16:19], v[178:181], v[202:205], v[16:19]
	v_mfma_f32_16x16x32_bf16 v[4:7], v[170:173], v[210:213], v[4:7]
	v_mfma_f32_16x16x32_bf16 v[0:3], v[178:181], v[210:213], v[0:3]
	s_setprio 0
	s_barrier
	s_add_i32 s74, 0, 0x18000
	s_add_i32 s75, 0, 0x1c000
	v_add_u32_e32 v162, s74, v156
	v_add_u32_e32 v178, s75, v156
	v_add_u32_e32 v230, s74, v227
	v_add_u32_e32 v231, s75, v227
	ds_read_b128 v[144:147], v162
	ds_read_b128 v[148:151], v230
	ds_read_b128 v[152:155], v162 offset:2048
	ds_read_b128 v[162:165], v230 offset:2048
	ds_read_b128 v[166:169], v178
	ds_read_b128 v[170:173], v231
	ds_read_b128 v[174:177], v178 offset:2048
	ds_read_b128 v[178:181], v231 offset:2048
	s_add_u32 s46, s46, 0x40000
	s_addc_u32 s47, s47, 0
	s_mov_b32 m0, s55
	v_lshl_add_u64 v[222:223], s[46:47], 0, v[128:129]
	ds_read_b128 v[182:185], v159 offset:32768
	ds_read_b128 v[186:189], v226 offset:32768
	ds_read_b128 v[190:193], v159 offset:34816
	ds_read_b128 v[194:197], v226 offset:34816
	ds_read_b128 v[198:201], v159 offset:36864
	ds_read_b128 v[202:205], v226 offset:36864
	ds_read_b128 v[206:209], v159 offset:38912
	ds_read_b128 v[210:213], v226 offset:38912
	global_load_lds_dwordx4 v[222:223], off
	v_lshl_add_u64 v[222:223], s[46:47], 0, v[132:133]
	s_mov_b32 m0, s56
	s_nop 0
	global_load_lds_dwordx4 v[222:223], off
	s_waitcnt vmcnt(8)
	s_waitcnt lgkmcnt(0)
	s_barrier
	s_setprio 1
	s_waitcnt lgkmcnt(0)
	v_mfma_f32_16x16x32_bf16 v[124:127], v[144:147], v[182:185], v[124:127]
	v_mfma_f32_16x16x32_bf16 v[120:123], v[152:155], v[182:185], v[120:123]
	v_mfma_f32_16x16x32_bf16 v[108:111], v[144:147], v[190:193], v[108:111]
	v_mfma_f32_16x16x32_bf16 v[104:107], v[152:155], v[190:193], v[104:107]
	v_mfma_f32_16x16x32_bf16 v[92:95], v[144:147], v[198:201], v[92:95]
	v_mfma_f32_16x16x32_bf16 v[88:91], v[152:155], v[198:201], v[88:91]
	v_mfma_f32_16x16x32_bf16 v[76:79], v[144:147], v[206:209], v[76:79]
	v_mfma_f32_16x16x32_bf16 v[72:75], v[152:155], v[206:209], v[72:75]
	v_mfma_f32_16x16x32_bf16 v[124:127], v[148:151], v[186:189], v[124:127]
	v_mfma_f32_16x16x32_bf16 v[120:123], v[162:165], v[186:189], v[120:123]
	v_mfma_f32_16x16x32_bf16 v[108:111], v[148:151], v[194:197], v[108:111]
	v_mfma_f32_16x16x32_bf16 v[104:107], v[162:165], v[194:197], v[104:107]
	v_mfma_f32_16x16x32_bf16 v[92:95], v[148:151], v[202:205], v[92:95]
	v_mfma_f32_16x16x32_bf16 v[88:91], v[162:165], v[202:205], v[88:91]
	v_mfma_f32_16x16x32_bf16 v[76:79], v[148:151], v[210:213], v[76:79]
	v_mfma_f32_16x16x32_bf16 v[72:75], v[162:165], v[210:213], v[72:75]
	s_setprio 0
	s_setprio 1
	v_mfma_f32_16x16x32_bf16 v[116:119], v[166:169], v[182:185], v[116:119]
	v_mfma_f32_16x16x32_bf16 v[112:115], v[174:177], v[182:185], v[112:115]
	v_mfma_f32_16x16x32_bf16 v[100:103], v[166:169], v[190:193], v[100:103]
	v_mfma_f32_16x16x32_bf16 v[96:99], v[174:177], v[190:193], v[96:99]
	v_mfma_f32_16x16x32_bf16 v[84:87], v[166:169], v[198:201], v[84:87]
	v_mfma_f32_16x16x32_bf16 v[80:83], v[174:177], v[198:201], v[80:83]
	v_mfma_f32_16x16x32_bf16 v[68:71], v[166:169], v[206:209], v[68:71]
	v_mfma_f32_16x16x32_bf16 v[64:67], v[174:177], v[206:209], v[64:67]
	v_mfma_f32_16x16x32_bf16 v[116:119], v[170:173], v[186:189], v[116:119]
	v_mfma_f32_16x16x32_bf16 v[112:115], v[178:181], v[186:189], v[112:115]
	v_mfma_f32_16x16x32_bf16 v[100:103], v[170:173], v[194:197], v[100:103]
	v_mfma_f32_16x16x32_bf16 v[96:99], v[178:181], v[194:197], v[96:99]
	v_mfma_f32_16x16x32_bf16 v[84:87], v[170:173], v[202:205], v[84:87]
	v_mfma_f32_16x16x32_bf16 v[80:83], v[178:181], v[202:205], v[80:83]
	v_mfma_f32_16x16x32_bf16 v[68:71], v[170:173], v[210:213], v[68:71]
	v_mfma_f32_16x16x32_bf16 v[64:67], v[178:181], v[210:213], v[64:67]
	s_setprio 0
	s_barrier
; #define PG8_STAGE(bufoff, gbase, voff) do { _Pragma("unroll") for (int _i = 0; _i < 2; ++_i) \
;         __builtin_amdgcn_global_load_lds((const unsigned*)((const char*)(gbase) + (voff)[_i]), (LAS unsigned*)(lds + (bufoff) + ldsw + _i * 8192), 16, 0, 0); } while (0)
; #define PG8_LDA(dst, b, h) do { _Pragma("unroll") for (int m = 0; m < 4; ++m) _Pragma("unroll") for (int k = 0; k < 2; ++k) dst[m][k] = *(const LAS bf16x8*)(lds + PG8_SA(b, h) + aoff + m * 2048 + k * 1024); } while (0)
; #define PG8_MMA(ai, bj, At, Bt) do { __builtin_amdgcn_s_setprio(1); _Pragma("unroll") for (int m = 0; m < 4; ++m) _Pragma("unroll") for (int n = 0; n < 2; ++n) _Pragma("unroll") for (int k = 0; k < 2; ++k) \
;         acc[ai][bj][m][n] = __builtin_amdgcn_mfma_f32_16x16x32_bf16(Bt[n][k], At[m][k], acc[ai][bj][m][n], 0, 0, 0); __builtin_amdgcn_s_setprio(0); } while (0)
; #define PG8_WAIT_V(n) asm volatile("s_waitcnt vmcnt(" #n ")" ::: "memory")
; #define PG8_WAIT_L(n) asm volatile("s_waitcnt lgkmcnt(" #n ")" ::: "memory")
; #define PG8_BAR __builtin_amdgcn_s_barrier()
; #define PG8_SCHED __builtin_amdgcn_sched_barrier(0)
; template <class Epi, class Sched>
; __device__ __forceinline__ void gemm_phase(LAS unsigned char* lds, const GemmP g, const Sched& S, const Epi& E, int tid) {
;     ...
;             PG8_LDA(At, 1, 1); PG8_STAGE(PG8_SB(1, 0), b3, voffB); PG8_STAGE(PG8_SB(1, 1), b3 + hstepB, voffB); PG8_STAGE(PG8_SA(1, 0), a3, voffA);
;             PG8_WAIT_V(8); PG8_WAIT_L(0); PG8_BAR; PG8_MMA(1, 0, At, B0); PG8_MMA(1, 1, At, B1); PG8_BAR; PG8_SCHED;
;         }
	s_add_i32 s46, s74, s52
	v_lshl_add_u64 v[214:215], v[214:215], 0, s[14:15]
	s_mov_b32 m0, s46
	ds_read_b128 v[182:185], v159 offset:49152
	ds_read_b128 v[186:189], v226 offset:49152
	ds_read_b128 v[190:193], v159 offset:51200
	ds_read_b128 v[194:197], v226 offset:51200
	ds_read_b128 v[198:201], v159 offset:53248
	ds_read_b128 v[202:205], v226 offset:53248
	ds_read_b128 v[206:209], v159 offset:55296
	ds_read_b128 v[210:213], v226 offset:55296
	global_load_lds_dwordx4 v[214:215], off
	s_add_i32 m0, s46, 0x2000
	s_add_u32 s44, s44, 0x40080
	v_lshl_add_u64 v[214:215], v[216:217], 0, s[14:15]
	s_addc_u32 s45, s45, 0
	s_add_i32 s46, s75, s52
	global_load_lds_dwordx4 v[214:215], off
	v_lshl_add_u64 v[214:215], s[44:45], 0, v[130:131]
	s_mov_b32 m0, s46
	s_nop 0
	global_load_lds_dwordx4 v[214:215], off
	v_lshl_add_u64 v[214:215], s[44:45], 0, v[134:135]
	s_add_i32 m0, s46, 0x2000
	s_nop 0
	global_load_lds_dwordx4 v[214:215], off
	v_lshl_add_u64 v[214:215], v[218:219], 0, s[14:15]
	s_mov_b32 m0, s62
	s_nop 0
	global_load_lds_dwordx4 v[214:215], off
	v_lshl_add_u64 v[214:215], v[220:221], 0, s[14:15]
	s_mov_b32 m0, s63
	s_nop 0
	global_load_lds_dwordx4 v[214:215], off
	s_waitcnt vmcnt(8)
	s_waitcnt lgkmcnt(0)
	s_barrier
	s_setprio 1
	s_waitcnt lgkmcnt(0)
	v_mfma_f32_16x16x32_bf16 v[60:63], v[144:147], v[182:185], v[60:63]
	v_mfma_f32_16x16x32_bf16 v[56:59], v[152:155], v[182:185], v[56:59]
	v_mfma_f32_16x16x32_bf16 v[44:47], v[144:147], v[190:193], v[44:47]
	v_mfma_f32_16x16x32_bf16 v[40:43], v[152:155], v[190:193], v[40:43]
	v_mfma_f32_16x16x32_bf16 v[28:31], v[144:147], v[198:201], v[28:31]
	v_mfma_f32_16x16x32_bf16 v[24:27], v[152:155], v[198:201], v[24:27]
	v_mfma_f32_16x16x32_bf16 v[12:15], v[144:147], v[206:209], v[12:15]
	v_mfma_f32_16x16x32_bf16 v[8:11], v[152:155], v[206:209], v[8:11]
	v_mfma_f32_16x16x32_bf16 v[60:63], v[148:151], v[186:189], v[60:63]
	v_mfma_f32_16x16x32_bf16 v[56:59], v[162:165], v[186:189], v[56:59]
	v_mfma_f32_16x16x32_bf16 v[44:47], v[148:151], v[194:197], v[44:47]
	v_mfma_f32_16x16x32_bf16 v[40:43], v[162:165], v[194:197], v[40:43]
	v_mfma_f32_16x16x32_bf16 v[28:31], v[148:151], v[202:205], v[28:31]
	v_mfma_f32_16x16x32_bf16 v[24:27], v[162:165], v[202:205], v[24:27]
	v_mfma_f32_16x16x32_bf16 v[12:15], v[148:151], v[210:213], v[12:15]
	v_mfma_f32_16x16x32_bf16 v[8:11], v[162:165], v[210:213], v[8:11]
	s_setprio 0
	s_setprio 1
	v_mfma_f32_16x16x32_bf16 v[52:55], v[166:169], v[182:185], v[52:55]
	v_mfma_f32_16x16x32_bf16 v[48:51], v[174:177], v[182:185], v[48:51]
	v_mfma_f32_16x16x32_bf16 v[36:39], v[166:169], v[190:193], v[36:39]
	v_mfma_f32_16x16x32_bf16 v[32:35], v[174:177], v[190:193], v[32:35]
	v_mfma_f32_16x16x32_bf16 v[20:23], v[166:169], v[198:201], v[20:23]
	v_mfma_f32_16x16x32_bf16 v[16:19], v[174:177], v[198:201], v[16:19]
	v_mfma_f32_16x16x32_bf16 v[4:7], v[166:169], v[206:209], v[4:7]
	v_mfma_f32_16x16x32_bf16 v[0:3], v[174:177], v[206:209], v[0:3]
	v_mfma_f32_16x16x32_bf16 v[52:55], v[170:173], v[186:189], v[52:55]
	v_mfma_f32_16x16x32_bf16 v[48:51], v[178:181], v[186:189], v[48:51]
	v_mfma_f32_16x16x32_bf16 v[36:39], v[170:173], v[194:197], v[36:39]
	v_mfma_f32_16x16x32_bf16 v[32:35], v[178:181], v[194:197], v[32:35]
	v_mfma_f32_16x16x32_bf16 v[20:23], v[170:173], v[202:205], v[20:23]
	v_mfma_f32_16x16x32_bf16 v[16:19], v[178:181], v[202:205], v[16:19]
	v_mfma_f32_16x16x32_bf16 v[4:7], v[170:173], v[210:213], v[4:7]
	v_mfma_f32_16x16x32_bf16 v[0:3], v[178:181], v[210:213], v[0:3]
	s_setprio 0
	s_barrier
	s_add_i32 s73, s73, 2
	s_add_u32 s71, s71, 0x100
	s_addc_u32 s72, s72, 0
	s_add_u32 s4, s4, 0x100
	s_addc_u32 s5, s5, 0
	s_cmp_gt_u32 s73, 13
	s_cbranch_scc0 .LBB0_166
	s_and_b64 vcc, exec, s[16:17]
	s_cbranch_vccz .LBB0_169
	s_barrier

; #define PG8_STAGE(bufoff, gbase, voff) do { _Pragma("unroll") for (int _i = 0; _i < 2; ++_i) \
;         __builtin_amdgcn_global_load_lds((const unsigned*)((const char*)(gbase) + (voff)[_i]), (LAS unsigned*)(lds + (bufoff) + ldsw + _i * 8192), 16, 0, 0); } while (0)
; #define PG8_BAR __builtin_amdgcn_s_barrier()
; template <class Epi, class Sched>
; __device__ __forceinline__ void gemm_phase(LAS unsigned char* lds, const GemmP g, const Sched& S, const Epi& E, int tid) {
;     ...
;     unsigned voffA[2], voffB[2];
; #pragma unroll
;     for (int i = 0; i < 2; ++i) { int R, C; stage_rc(tid * 16 + i * 8192, R, C); const int Rb = (R & ~31) + perm32(R & 31);
;         voffA[i] = (unsigned)(R * g.lda + C) * 2u; voffB[i] = (unsigned)(Rb * g.ldb + C) * 2u; }
;     ...
;     PG8_STAGE(PG8_SB(0, 0), cB, voffB); PG8_STAGE(PG8_SB(0, 1), cB + hstepB, voffB); PG8_STAGE(PG8_SA(0, 0), cA, voffA); PG8_STAGE(PG8_SA(0, 1), cA + hstepA, voffA);
;     if (wr == 1) PG8_BAR;
.LBB0_1381:
	s_andn2_b64 vcc, exec, s[2:3]
	s_cbranch_vccnz .LBB0_1451
	v_ashrrev_i32_e32 v2, 31, v0
	v_lshrrev_b32_e32 v2, 26, v2
	v_lshlrev_b32_e32 v1, 4, v0
	v_add_u32_e32 v2, v0, v2
	v_bfe_i32 v0, v0, 27, 1
	v_lshrrev_b32_e32 v0, 22, v0
	v_add_u32_e32 v0, v1, v0
	v_and_b32_e32 v0, 0xfffffc00, v0
	v_sub_u32_e32 v0, v1, v0
	v_ashrrev_i32_e32 v9, 6, v2
	v_lshrrev_b32_e32 v2, 4, v0
	v_bitop3_b32 v2, v2, v0, 32 bitop3:0x6c
	v_ashrrev_i32_e32 v0, 31, v0
	v_lshrrev_b32_e32 v0, 26, v0
	v_add_u32_e32 v0, v2, v0
	v_lshlrev_b32_e32 v3, 3, v9
	v_ashrrev_i32_e32 v10, 6, v0
	v_and_b32_e32 v0, 0xc0, v0
	v_and_b32_e32 v3, -16, v3
	v_sub_u32_e32 v0, v2, v0
	v_add_u32_e32 v3, v10, v3
	v_ashrrev_i16_sdwa v0, v219, sext(v0) dst_sel:DWORD dst_unused:UNUSED_PAD src0_sel:DWORD src1_sel:BYTE_0
	v_lshlrev_b32_e32 v4, 5, v9
	v_bfe_i32 v11, v0, 0, 16
	v_lshlrev_b32_e32 v0, 1, v3
	v_lshrrev_b32_e32 v2, 2, v3
	v_and_b32_e32 v5, 3, v10
	s_mov_b32 s2, 0x1fffe0
	v_and_b32_e32 v4, 32, v4
	v_and_b32_e32 v0, 24, v0
	v_and_b32_e32 v2, 4, v2
	v_and_or_b32 v5, v3, s2, v5
	v_or3_b32 v0, v5, v2, v0
	v_add_lshl_u32 v2, v4, v11, 1
	v_lshl_add_u32 v130, v0, 11, v2
	v_add_u32_e32 v0, 0x2000, v1
	v_ashrrev_i32_e32 v1, 31, v0
	v_lshrrev_b32_e32 v1, 22, v1
	v_add_u32_e32 v1, v0, v1
	v_ashrrev_i32_e32 v12, 10, v1
	v_mul_i32_i24_e32 v1, 0x400, v12
	v_sub_u32_e32 v0, v0, v1
	v_lshrrev_b32_e32 v1, 4, v0
	v_bitop3_b32 v0, v1, v0, 32 bitop3:0x6c
	v_lshl_add_u32 v128, v3, 11, v2
	v_ashrrev_i32_e32 v2, 31, v0
	v_lshrrev_b32_e32 v2, 26, v2
	v_lshlrev_b32_e32 v1, 3, v12
	v_add_u32_e32 v2, v0, v2
	v_and_b32_e32 v1, -16, v1
	v_ashrrev_i32_e32 v13, 6, v2
	v_add_u32_e32 v1, v13, v1
	v_and_b32_e32 v2, 0xc0, v2
	v_and_b32_e32 v4, 3, v13
	v_sub_u32_e32 v0, v0, v2
	v_and_or_b32 v4, v1, s2, v4
	s_ashr_i32 s2, s14, 6
	v_ashrrev_i16_sdwa v0, v219, sext(v0) dst_sel:DWORD dst_unused:UNUSED_PAD src0_sel:DWORD src1_sel:BYTE_0
	s_lshl_b32 s52, s2, 10
	v_lshlrev_b32_e32 v3, 5, v12
	v_bfe_i32 v14, v0, 0, 16
	v_lshlrev_b32_e32 v0, 1, v1
	v_lshrrev_b32_e32 v2, 2, v1
	s_add_i32 s53, s52, 0
	v_and_b32_e32 v3, 32, v3
	v_and_b32_e32 v0, 24, v0
	v_and_b32_e32 v2, 4, v2
	s_add_i32 m0, s53, 0x10000
	s_ashr_i32 s15, s14, 8
	v_or3_b32 v0, v4, v2, v0
	v_add_lshl_u32 v2, v3, v14, 1
	v_lshrrev_b32_e32 v232, 3, v8
	v_lshrrev_b32_e32 v233, 4, v8
	v_and_b32_e32 v234, 7, v8
	v_xor_b32_e32 v234, v234, v233
	s_and_b32 s32, s2, 1
	s_lshl_b32 s57, s32, 2
	v_xor_b32_e32 v234, s57, v234
	v_lshlrev_b32_e32 v234, 4, v234
	s_lshl_b32 s57, s2, 3
	v_add_u32_e32 v235, s57, v232
	v_lshl_or_b32 v128, v235, 11, v234
	v_add_u32_e32 v132, 0x20000, v128
	s_lshr_b32 s57, s2, 2
	s_lshl_b32 s57, s57, 5
	s_lshl_b32 s98, s32, 4
	s_add_i32 s57, s57, s98
	s_bfe_u32 s98, s2, 0x10001
	s_lshl_b32 s98, s98, 2
	s_add_i32 s57, s57, s98
	v_lshrrev_b32_e32 v235, 5, v8
	v_and_b32_e32 v232, 3, v232
	v_lshl_or_b32 v235, v235, 3, v232
	v_add_u32_e32 v235, s57, v235
	v_lshl_or_b32 v130, v235, 11, v234
	v_add_u32_e32 v134, 0x20000, v130
	global_load_lds_dwordx4 v130, s[12:13]
	s_add_i32 m0, s53, 0x12000
	s_add_u32 s18, s12, 0x40000
	global_load_lds_dwordx4 v134, s[12:13]
	s_addc_u32 s19, s13, 0
	s_add_i32 m0, s53, 0x14000
	s_add_i32 s54, s53, 0x2000
	global_load_lds_dwordx4 v130, s[18:19]
	s_add_i32 m0, s53, 0x16000
	s_nop 0
	global_load_lds_dwordx4 v134, s[18:19]
	s_mov_b32 m0, s53
	s_add_u32 s18, s10, 0x40000
	global_load_lds_dwordx4 v128, s[10:11]
	s_mov_b32 m0, s54
	s_addc_u32 s19, s11, 0
	s_add_i32 s58, s53, 0x4000
	global_load_lds_dwordx4 v132, s[10:11]
	s_mov_b32 m0, s58
	s_add_i32 s59, s53, 0x6000
	global_load_lds_dwordx4 v128, s[18:19]
	s_mov_b32 m0, s59
	v_writelane_b32 v255, s70, 27
	global_load_lds_dwordx4 v132, s[18:19]
	v_mov_b32_e32 v131, v197
	v_mov_b32_e32 v135, v197
	v_mov_b32_e32 v129, v197
	v_mov_b32_e32 v133, v197
	s_cmp_eq_u32 s15, 1
	v_writelane_b32 v255, s71, 28
	v_lshl_add_u64 v[6:7], s[12:13], 0, v[130:131]
	v_lshl_add_u64 v[4:5], s[12:13], 0, v[134:135]
	v_lshl_add_u64 v[0:1], s[10:11], 0, v[128:129]
	s_cselect_b64 s[18:19], -1, 0
	s_cmp_lg_u32 s15, 1
	v_lshl_add_u64 v[2:3], s[10:11], 0, v[132:133]
	s_cbranch_scc1 .LBB0_1384
	s_barrier
; #define PG8_STAGE(bufoff, gbase, voff) do { _Pragma("unroll") for (int _i = 0; _i < 2; ++_i) \
;         __builtin_amdgcn_global_load_lds((const unsigned*)((const char*)(gbase) + (voff)[_i]), (LAS unsigned*)(lds + (bufoff) + ldsw + _i * 8192), 16, 0, 0); } while (0)
; #define PG8_WAIT_V(n) asm volatile("s_waitcnt vmcnt(" #n ")" ::: "memory")
; #define PG8_BAR __builtin_amdgcn_s_barrier()
; template <class Epi, class Sched>
; __device__ __forceinline__ void gemm_phase(LAS unsigned char* lds, const GemmP g, const Sched& S, const Epi& E, int tid) {
;     ...
;     const size_t kstep = (size_t)(BK * 2);
;     const size_t hstepA = (size_t)HALF * g.lda * 2, hstepB = (size_t)HALF * g.ldb * 2;
;     const unsigned ldsw = (unsigned)wid * 1024u;
;     const int aoff = lds_byte(wr * 64 + fr, fq * 8), boff = lds_byte(wc * 32 + fr, fq * 8);
;     ...
;     PG8_WAIT_V(2); PG8_BAR;
;     PG8_STAGE(PG8_SB(1, 0), cB + kstep, voffB); PG8_STAGE(PG8_SA(1, 0), cA + kstep, voffA); PG8_STAGE(PG8_SB(1, 1), cB + hstepB + kstep, voffB);
;     PG8_WAIT_V(6); PG8_BAR;
.LBB0_1384:
	s_add_u32 s20, s6, 0x13000000
	v_readlane_b32 s29, v255, 18
	s_addc_u32 s21, s7, 0
	s_mul_i32 s22, s29, 0x10800
	s_mul_hi_i32 s3, s29, 0x10800
	s_add_u32 s38, s6, s22
	s_addc_u32 s39, s7, s3
	s_add_u32 s22, s38, 0x3ba00000
	s_addc_u32 s23, s39, 0
	s_mul_i32 s24, s29, 0x5800
	s_mul_hi_i32 s3, s29, 0x5800
	s_add_u32 s44, s6, s24
	s_addc_u32 s45, s7, s3
	s_add_u32 s24, s44, 0x3ba40000
	s_addc_u32 s25, s45, 0
	s_mul_i32 s28, s29, 0x160000
	s_mul_hi_i32 s3, s29, 0x160000
	s_waitcnt lgkmcnt(0)
	s_add_u32 s26, s0, s28
	s_addc_u32 s27, s1, s3
	s_mul_i32 s1, s29, 0xb0000
	s_mul_hi_i32 s0, s29, 0xb0000
	s_add_u32 s1, s4, s1
	s_addc_u32 s0, s5, s0
	s_add_u32 s70, s1, 0x31ad0000
	s_addc_u32 s71, s0, 0
	s_add_u32 s0, s4, s28
	s_addc_u32 s1, s5, s3
	s_add_u32 s30, s0, 0x31c30000
	s_addc_u32 s31, s1, 0
	s_add_u32 s34, s6, 0x2bc00000
	s_addc_u32 s35, s7, 0
	s_add_u32 s36, s6, 0x2c800000
	s_addc_u32 s37, s7, 0
	s_cmp_eq_u32 s29, 0
	s_mov_b32 s0, 0x84000
	s_cselect_b32 s0, s0, 0x14a000
	s_add_u32 s0, s6, s0
	s_addc_u32 s1, s7, 0
	s_add_u32 s46, s0, 0x35800000
	v_and_b32_e32 v15, 15, v8
	v_and_b32_e32 v16, 48, v8
	v_lshlrev_b32_e32 v8, 2, v8
	s_addc_u32 s47, s1, 0
	s_lshl_b32 s0, s15, 13
	v_lshl_or_b32 v15, v15, 6, v16
	v_and_b32_e32 v8, 32, v8
	v_bitop3_b32 v16, v15, s0, v8 bitop3:0xde
	s_lshl_b32 s0, s2, 5
	s_and_b32 s88, s0, 0x60
	s_add_i32 m0, s53, 0x18000
	v_lshl_add_u64 v[6:7], v[6:7], 0, s[80:81]
	s_lshl_b32 s29, s15, 6
	s_lshl_b32 s0, s88, 7
	s_waitcnt vmcnt(2)
	s_barrier
	global_load_lds_dwordx4 v[6:7], off
	v_lshl_add_u64 v[4:5], v[4:5], 0, s[80:81]
	s_add_i32 m0, s53, 0x1a000
	s_add_i32 s89, s53, 0x8000
	s_add_i32 s64, s53, 0xa000
	v_bitop3_b32 v146, s0, v15, v8 bitop3:0xf6
	global_load_lds_dwordx4 v[4:5], off
	v_lshl_add_u64 v[0:1], v[0:1], 0, s[80:81]
	s_mov_b32 m0, s89
	s_add_u32 s0, s12, 0x40080
	global_load_lds_dwordx4 v[0:1], off
	v_lshl_add_u64 v[0:1], v[2:3], 0, s[80:81]
	s_mov_b32 m0, s64
	s_addc_u32 s1, s13, 0
	global_load_lds_dwordx4 v[0:1], off
	s_add_i32 m0, s53, 0x1c000
	v_lshl_add_u64 v[0:1], s[0:1], 0, v[130:131]
	global_load_lds_dwordx4 v[0:1], off
	v_lshl_add_u64 v[0:1], s[0:1], 0, v[134:135]
	s_add_i32 m0, s53, 0x1e000
	s_cmpk_lt_u32 s14, 0x100
	global_load_lds_dwordx4 v[0:1], off
	s_cselect_b64 s[2:3], -1, 0
	s_lshl_b32 s4, s15, 1
	s_add_i32 s65, s4, 0x3ffff2
	s_add_i32 s0, s4, -2
	s_cmp_gt_i32 s15, 0
	s_cselect_b32 s66, s0, 0
	s_cmpk_gt_u32 s14, 0xff
	s_cselect_b64 s[0:1], -1, 0
	s_add_i32 s4, s4, 2
	s_cmp_gt_i32 s15, -2
	s_cselect_b32 s67, s4, 0
	s_ashr_i32 s68, s40, 31
	s_ashr_i32 s69, s41, 31
	s_add_u32 s44, s44, 0x3ba42c00
	s_addc_u32 s45, s45, 0
	s_add_u32 s76, s38, 0x3ba02c00
	s_addc_u32 s77, s39, 0
	v_lshlrev_b32_e32 v0, 14, v12
	s_add_u32 s78, s38, 0x3ba05800
	v_and_b32_e32 v0, 0xffff8000, v0
	s_addc_u32 s79, s39, 0
	v_lshl_add_u32 v0, v13, 11, v0
	v_and_b32_e32 v1, 1, v12
	s_add_u32 s84, s38, 0x3ba08400
	v_lshl_or_b32 v0, v1, 6, v0
	s_addc_u32 s85, s39, 0
	v_lshl_add_u32 v136, v14, 1, v0
	v_lshlrev_b32_e32 v0, 14, v9
	s_add_u32 s86, s38, 0x3ba0b000
	v_and_b32_e32 v0, 0xffff8000, v0
	s_waitcnt vmcnt(6)
	s_addc_u32 s87, s39, 0
	v_lshl_add_u32 v0, v10, 11, v0
	v_and_b32_e32 v1, 1, v9
	s_add_u32 s92, s38, 0x3ba0dc00
	v_lshl_or_b32 v0, v1, 6, v0
	s_mov_b32 s28, 0
	s_addc_u32 s93, s39, 0
	v_mov_b32_e32 v137, v197
	v_lshl_add_u32 v138, v11, 1, v0
	v_mov_b32_e32 v139, v197
	v_add_u32_e32 v147, 0, v16
	s_mov_b64 s[96:97], s[12:13]
	s_mov_b64 s[94:95], s[10:11]
	v_mbcnt_lo_u32_b32 v232, -1, 0
	v_mbcnt_hi_u32_b32 v232, -1, v232
	v_and_b32_e32 v233, 15, v232
	v_lshrrev_b32_e32 v234, 4, v232
	v_lshrrev_b32_e32 v235, 3, v233
	v_bfe_u32 v236, v233, 1, 2
	v_xor_b32_e32 v236, v236, v234
	v_lshl_or_b32 v236, v235, 2, v236
	v_lshlrev_b32_e32 v236, 4, v236
	v_and_b32_e32 v237, 7, v233
	v_lshl_or_b32 v236, v237, 7, v236
	v_lshl_or_b32 v236, v235, 10, v236
	s_lshr_b32 s32, s52, 12
	s_lshl_b32 s32, s32, 13
	s_bfe_u32 s57, s52, 0x2000a
	s_lshl_b32 s57, s57, 12
	v_add_u32_e32 v147, s32, v236
	v_add_u32_e32 v146, s57, v236
	v_xor_b32_e32 v230, 64, v147
	v_xor_b32_e32 v231, 64, v146
	v_mov_b32_e32 v136, v132
	v_mov_b32_e32 v138, v128
	s_barrier
	s_branch .LBB0_1387

; #define PG8_STAGE(bufoff, gbase, voff) do { _Pragma("unroll") for (int _i = 0; _i < 2; ++_i) \
;         __builtin_amdgcn_global_load_lds((const unsigned*)((const char*)(gbase) + (voff)[_i]), (LAS unsigned*)(lds + (bufoff) + ldsw + _i * 8192), 16, 0, 0); } while (0)
; #define PG8_LDA(dst, b, h) do { _Pragma("unroll") for (int m = 0; m < 4; ++m) _Pragma("unroll") for (int k = 0; k < 2; ++k) dst[m][k] = *(const LAS bf16x8*)(lds + PG8_SA(b, h) + aoff + m * 2048 + k * 1024); } while (0)
; #define PG8_LDB(dst, b, h) do { _Pragma("unroll") for (int n = 0; n < 2; ++n) _Pragma("unroll") for (int k = 0; k < 2; ++k) dst[n][k] = *(const LAS bf16x8*)(lds + PG8_SB(b, h) + boff + n * 2048 + k * 1024); } while (0)
; #define PG8_MMA(ai, bj, At, Bt) do { __builtin_amdgcn_s_setprio(1); _Pragma("unroll") for (int m = 0; m < 4; ++m) _Pragma("unroll") for (int n = 0; n < 2; ++n) _Pragma("unroll") for (int k = 0; k < 2; ++k) \
;         acc[ai][bj][m][n] = __builtin_amdgcn_mfma_f32_16x16x32_bf16(Bt[n][k], At[m][k], acc[ai][bj][m][n], 0, 0, 0); __builtin_amdgcn_s_setprio(0); } while (0)
; #define PG8_WAIT_V(n) asm volatile("s_waitcnt vmcnt(" #n ")" ::: "memory")
; #define PG8_WAIT_L(n) asm volatile("s_waitcnt lgkmcnt(" #n ")" ::: "memory")
; #define PG8_BAR __builtin_amdgcn_s_barrier()
; #define PG8_SCHED __builtin_amdgcn_sched_barrier(0)
; template <class Epi, class Sched>
; __device__ __forceinline__ void gemm_phase(LAS unsigned char* lds, const GemmP g, const Sched& S, const Epi& E, int tid) {
;     ...
;             const bool last = (t == nt - 2);
;             const char* a1 = cA + (size_t)(t + 1) * kstep;
;             const char* a2 = last ? nA : cA + (size_t)(t + 2) * kstep; const char* b2 = last ? nB : cB + (size_t)(t + 2) * kstep;
;             const char* a3 = a2 + kstep; const char* b3 = b2 + kstep;
;             PG8_LDB(B0, 0, 0); PG8_LDB(B1, 0, 1); PG8_SCHED; PG8_LDA(At, 0, 0); PG8_STAGE(PG8_SA(1, 1), a1 + hstepA, voffA);
;             PG8_WAIT_V(8); PG8_WAIT_L(0); PG8_BAR; PG8_MMA(0, 0, At, B0); PG8_MMA(0, 1, At, B1); PG8_BAR; PG8_SCHED;
;             PG8_LDA(At, 0, 1); PG8_STAGE(PG8_SB(0, 0), b2, voffB); PG8_STAGE(PG8_SB(0, 1), b2 + hstepB, voffB); PG8_STAGE(PG8_SA(0, 0), a2, voffA);
.LBB0_1390:
	s_add_u32 s10, s6, 0xfffc0080
	s_addc_u32 s11, s7, -1
	s_add_i32 s39, 0, 0x10000
	s_cmp_eq_u32 s38, 12
	s_cselect_b32 s13, s95, s11
	s_cselect_b32 s12, s94, s10
	v_add_u32_e32 v144, s39, v146
	v_add_u32_e32 v232, s39, v231
	s_cselect_b32 s11, s97, s15
	s_cselect_b32 s10, s96, s14
	s_add_i32 s56, 0, 0x14000
	ds_read_b128 v[140:143], v144
	ds_read_b128 v[148:151], v232
	ds_read_b128 v[152:155], v144 offset:2048
	ds_read_b128 v[156:159], v232 offset:2048
	v_add_u32_e32 v144, s56, v146
	v_add_u32_e32 v233, s56, v231
	ds_read_b128 v[160:163], v144
	ds_read_b128 v[164:167], v233
	ds_read_b128 v[168:171], v144 offset:2048
	ds_read_b128 v[172:175], v233 offset:2048
	v_lshl_add_u64 v[144:145], s[6:7], 0, v[138:139]
	s_add_i32 m0, s53, 0xc000
	ds_read_b128 v[176:179], v147
	ds_read_b128 v[180:183], v230
	ds_read_b128 v[184:187], v147 offset:2048
	ds_read_b128 v[188:191], v230 offset:2048
	ds_read_b128 v[192:195], v147 offset:4096
	ds_read_b128 v[206:209], v230 offset:4096
	ds_read_b128 v[210:213], v147 offset:6144
	ds_read_b128 v[214:217], v230 offset:6144
	global_load_lds_dwordx4 v[144:145], off
	v_lshl_add_u64 v[144:145], s[6:7], 0, v[136:137]
	s_add_i32 m0, s53, 0xe000
	s_nop 0
	global_load_lds_dwordx4 v[144:145], off
	s_cmp_eq_u32 s38, -2
	s_cbranch_scc1 .Lfirstit_5
	s_waitcnt vmcnt(8)
.Lfirstit_5:
	s_waitcnt lgkmcnt(0)
	s_barrier
	s_setprio 1
	s_waitcnt lgkmcnt(0)
	v_mfma_f32_16x16x32_bf16 v[92:95], v[140:143], v[176:179], v[92:95]
	v_mfma_f32_16x16x32_bf16 v[88:91], v[152:155], v[176:179], v[88:91]
	v_mfma_f32_16x16x32_bf16 v[76:79], v[140:143], v[184:187], v[76:79]
	v_mfma_f32_16x16x32_bf16 v[72:75], v[152:155], v[184:187], v[72:75]
	v_mfma_f32_16x16x32_bf16 v[60:63], v[140:143], v[192:195], v[60:63]
	v_mfma_f32_16x16x32_bf16 v[56:59], v[152:155], v[192:195], v[56:59]
	v_mfma_f32_16x16x32_bf16 v[124:127], v[140:143], v[210:213], v[124:127]
	v_mfma_f32_16x16x32_bf16 v[120:123], v[152:155], v[210:213], v[120:123]
	v_mfma_f32_16x16x32_bf16 v[92:95], v[148:151], v[180:183], v[92:95]
	v_mfma_f32_16x16x32_bf16 v[88:91], v[156:159], v[180:183], v[88:91]
	v_mfma_f32_16x16x32_bf16 v[76:79], v[148:151], v[188:191], v[76:79]
	v_mfma_f32_16x16x32_bf16 v[72:75], v[156:159], v[188:191], v[72:75]
	v_mfma_f32_16x16x32_bf16 v[60:63], v[148:151], v[206:209], v[60:63]
	v_mfma_f32_16x16x32_bf16 v[56:59], v[156:159], v[206:209], v[56:59]
	v_mfma_f32_16x16x32_bf16 v[124:127], v[148:151], v[214:217], v[124:127]
	v_mfma_f32_16x16x32_bf16 v[120:123], v[156:159], v[214:217], v[120:123]
	s_setprio 0
	s_setprio 1
	v_mfma_f32_16x16x32_bf16 v[84:87], v[160:163], v[176:179], v[84:87]
	v_mfma_f32_16x16x32_bf16 v[80:83], v[168:171], v[176:179], v[80:83]
	v_mfma_f32_16x16x32_bf16 v[68:71], v[160:163], v[184:187], v[68:71]
	v_mfma_f32_16x16x32_bf16 v[64:67], v[168:171], v[184:187], v[64:67]
	v_mfma_f32_16x16x32_bf16 v[52:55], v[160:163], v[192:195], v[52:55]
	v_mfma_f32_16x16x32_bf16 v[48:51], v[168:171], v[192:195], v[48:51]
	v_mfma_f32_16x16x32_bf16 v[116:119], v[160:163], v[210:213], v[116:119]
	v_mfma_f32_16x16x32_bf16 v[112:115], v[168:171], v[210:213], v[112:115]
	v_mfma_f32_16x16x32_bf16 v[84:87], v[164:167], v[180:183], v[84:87]
	v_mfma_f32_16x16x32_bf16 v[80:83], v[172:175], v[180:183], v[80:83]
	v_mfma_f32_16x16x32_bf16 v[68:71], v[164:167], v[188:191], v[68:71]
	v_mfma_f32_16x16x32_bf16 v[64:67], v[172:175], v[188:191], v[64:67]
	v_mfma_f32_16x16x32_bf16 v[52:55], v[164:167], v[206:209], v[52:55]
	v_mfma_f32_16x16x32_bf16 v[48:51], v[172:175], v[206:209], v[48:51]
	v_mfma_f32_16x16x32_bf16 v[116:119], v[164:167], v[214:217], v[116:119]
	v_mfma_f32_16x16x32_bf16 v[112:115], v[172:175], v[214:217], v[112:115]
	s_setprio 0
	s_barrier
	s_add_i32 s39, s39, s52
	v_lshl_add_u64 v[144:145], s[10:11], 0, v[130:131]
	s_mov_b32 m0, s39
	ds_read_b128 v[176:179], v147 offset:16384
	ds_read_b128 v[180:183], v230 offset:16384
	ds_read_b128 v[184:187], v147 offset:18432
	ds_read_b128 v[188:191], v230 offset:18432
	ds_read_b128 v[192:195], v147 offset:20480
	ds_read_b128 v[206:209], v230 offset:20480
	ds_read_b128 v[210:213], v147 offset:22528
	ds_read_b128 v[214:217], v230 offset:22528
	global_load_lds_dwordx4 v[144:145], off
	s_add_i32 m0, s39, 0x2000
	s_add_u32 s48, s10, 0x40000
	v_lshl_add_u64 v[198:199], s[10:11], 0, v[134:135]
	s_addc_u32 s49, s11, 0
	s_add_i32 s39, s56, s52
	global_load_lds_dwordx4 v[198:199], off
	v_lshl_add_u64 v[200:201], s[48:49], 0, v[130:131]
	s_mov_b32 m0, s39
	v_lshl_add_u64 v[220:221], s[12:13], 0, v[132:133]
	global_load_lds_dwordx4 v[200:201], off
	v_lshl_add_u64 v[200:201], s[48:49], 0, v[134:135]
	s_add_i32 m0, s39, 0x2000
	s_nop 0
	global_load_lds_dwordx4 v[200:201], off
	v_lshl_add_u64 v[200:201], s[12:13], 0, v[128:129]
	s_mov_b32 m0, s53
	s_nop 0
	global_load_lds_dwordx4 v[200:201], off
	s_mov_b32 m0, s54
	s_nop 0
	global_load_lds_dwordx4 v[220:221], off
	s_waitcnt vmcnt(8)
	s_waitcnt lgkmcnt(0)
	s_barrier
; #define PG8_STAGE(bufoff, gbase, voff) do { _Pragma("unroll") for (int _i = 0; _i < 2; ++_i) \
;         __builtin_amdgcn_global_load_lds((const unsigned*)((const char*)(gbase) + (voff)[_i]), (LAS unsigned*)(lds + (bufoff) + ldsw + _i * 8192), 16, 0, 0); } while (0)
; #define PG8_LDA(dst, b, h) do { _Pragma("unroll") for (int m = 0; m < 4; ++m) _Pragma("unroll") for (int k = 0; k < 2; ++k) dst[m][k] = *(const LAS bf16x8*)(lds + PG8_SA(b, h) + aoff + m * 2048 + k * 1024); } while (0)
; #define PG8_LDB(dst, b, h) do { _Pragma("unroll") for (int n = 0; n < 2; ++n) _Pragma("unroll") for (int k = 0; k < 2; ++k) dst[n][k] = *(const LAS bf16x8*)(lds + PG8_SB(b, h) + boff + n * 2048 + k * 1024); } while (0)
; #define PG8_MMA(ai, bj, At, Bt) do { __builtin_amdgcn_s_setprio(1); _Pragma("unroll") for (int m = 0; m < 4; ++m) _Pragma("unroll") for (int n = 0; n < 2; ++n) _Pragma("unroll") for (int k = 0; k < 2; ++k) \
;         acc[ai][bj][m][n] = __builtin_amdgcn_mfma_f32_16x16x32_bf16(Bt[n][k], At[m][k], acc[ai][bj][m][n], 0, 0, 0); __builtin_amdgcn_s_setprio(0); } while (0)
; #define PG8_WAIT_V(n) asm volatile("s_waitcnt vmcnt(" #n ")" ::: "memory")
; #define PG8_WAIT_L(n) asm volatile("s_waitcnt lgkmcnt(" #n ")" ::: "memory")
; #define PG8_BAR __builtin_amdgcn_s_barrier()
; #define PG8_SCHED __builtin_amdgcn_sched_barrier(0)
; template <class Epi, class Sched>
; __device__ __forceinline__ void gemm_phase(LAS unsigned char* lds, const GemmP g, const Sched& S, const Epi& E, int tid) {
;     ...
;             PG8_WAIT_V(8); PG8_WAIT_L(0); PG8_BAR; PG8_MMA(1, 0, At, B0); PG8_MMA(1, 1, At, B1); PG8_BAR; PG8_SCHED;
;             PG8_LDB(B0, 1, 0); PG8_LDB(B1, 1, 1); PG8_SCHED; PG8_LDA(At, 1, 0); PG8_STAGE(PG8_SA(0, 1), a2 + hstepA, voffA);
;             PG8_WAIT_V(8); PG8_WAIT_L(0); PG8_BAR; PG8_MMA(0, 0, At, B0); PG8_MMA(0, 1, At, B1); PG8_BAR; PG8_SCHED;
	s_setprio 1
	s_waitcnt lgkmcnt(0)
	v_mfma_f32_16x16x32_bf16 v[44:47], v[140:143], v[176:179], v[44:47]
	v_mfma_f32_16x16x32_bf16 v[40:43], v[152:155], v[176:179], v[40:43]
	v_mfma_f32_16x16x32_bf16 v[28:31], v[140:143], v[184:187], v[28:31]
	v_mfma_f32_16x16x32_bf16 v[24:27], v[152:155], v[184:187], v[24:27]
	v_mfma_f32_16x16x32_bf16 v[12:15], v[140:143], v[192:195], v[12:15]
	v_mfma_f32_16x16x32_bf16 v[8:11], v[152:155], v[192:195], v[8:11]
	v_mfma_f32_16x16x32_bf16 v[108:111], v[140:143], v[210:213], v[108:111]
	v_mfma_f32_16x16x32_bf16 v[104:107], v[152:155], v[210:213], v[104:107]
	v_mfma_f32_16x16x32_bf16 v[44:47], v[148:151], v[180:183], v[44:47]
	v_mfma_f32_16x16x32_bf16 v[40:43], v[156:159], v[180:183], v[40:43]
	v_mfma_f32_16x16x32_bf16 v[28:31], v[148:151], v[188:191], v[28:31]
	v_mfma_f32_16x16x32_bf16 v[24:27], v[156:159], v[188:191], v[24:27]
	v_mfma_f32_16x16x32_bf16 v[12:15], v[148:151], v[206:209], v[12:15]
	v_mfma_f32_16x16x32_bf16 v[8:11], v[156:159], v[206:209], v[8:11]
	v_mfma_f32_16x16x32_bf16 v[108:111], v[148:151], v[214:217], v[108:111]
	v_mfma_f32_16x16x32_bf16 v[104:107], v[156:159], v[214:217], v[104:107]
	s_setprio 0
	s_setprio 1
	v_mfma_f32_16x16x32_bf16 v[36:39], v[160:163], v[176:179], v[36:39]
	v_mfma_f32_16x16x32_bf16 v[32:35], v[168:171], v[176:179], v[32:35]
	v_mfma_f32_16x16x32_bf16 v[20:23], v[160:163], v[184:187], v[20:23]
	v_mfma_f32_16x16x32_bf16 v[16:19], v[168:171], v[184:187], v[16:19]
	v_mfma_f32_16x16x32_bf16 v[4:7], v[160:163], v[192:195], v[4:7]
	v_mfma_f32_16x16x32_bf16 v[0:3], v[168:171], v[192:195], v[0:3]
	v_mfma_f32_16x16x32_bf16 v[100:103], v[160:163], v[210:213], v[100:103]
	v_mfma_f32_16x16x32_bf16 v[96:99], v[168:171], v[210:213], v[96:99]
	v_mfma_f32_16x16x32_bf16 v[36:39], v[164:167], v[180:183], v[36:39]
	v_mfma_f32_16x16x32_bf16 v[32:35], v[172:175], v[180:183], v[32:35]
	v_mfma_f32_16x16x32_bf16 v[20:23], v[164:167], v[188:191], v[20:23]
	v_mfma_f32_16x16x32_bf16 v[16:19], v[172:175], v[188:191], v[16:19]
	v_mfma_f32_16x16x32_bf16 v[4:7], v[164:167], v[206:209], v[4:7]
	v_mfma_f32_16x16x32_bf16 v[0:3], v[172:175], v[206:209], v[0:3]
	v_mfma_f32_16x16x32_bf16 v[100:103], v[164:167], v[214:217], v[100:103]
	v_mfma_f32_16x16x32_bf16 v[96:99], v[172:175], v[214:217], v[96:99]
	s_setprio 0
	s_barrier
	s_add_i32 s39, 0, 0x18000
	s_add_i32 s48, 0, 0x1c000
	v_add_u32_e32 v156, s39, v146
	v_add_u32_e32 v232, s39, v231
	v_add_u32_e32 v172, s48, v146
	v_add_u32_e32 v233, s48, v231
	ds_read_b128 v[140:143], v156
	ds_read_b128 v[148:151], v232
	ds_read_b128 v[152:155], v156 offset:2048
	ds_read_b128 v[156:159], v232 offset:2048
	ds_read_b128 v[160:163], v172
	ds_read_b128 v[164:167], v233
	ds_read_b128 v[168:171], v172 offset:2048
	ds_read_b128 v[172:175], v233 offset:2048
	s_add_u32 s12, s12, 0x40000
	s_addc_u32 s13, s13, 0
	s_mov_b32 m0, s58
	v_lshl_add_u64 v[222:223], s[12:13], 0, v[128:129]
	ds_read_b128 v[176:179], v147 offset:32768
	ds_read_b128 v[180:183], v230 offset:32768
	ds_read_b128 v[184:187], v147 offset:34816
	ds_read_b128 v[188:191], v230 offset:34816
	ds_read_b128 v[192:195], v147 offset:36864
	ds_read_b128 v[206:209], v230 offset:36864
	ds_read_b128 v[210:213], v147 offset:38912
	ds_read_b128 v[214:217], v230 offset:38912
	global_load_lds_dwordx4 v[222:223], off
	v_lshl_add_u64 v[222:223], s[12:13], 0, v[132:133]
	s_mov_b32 m0, s59
	s_nop 0
	global_load_lds_dwordx4 v[222:223], off
	s_waitcnt vmcnt(8)
	s_waitcnt lgkmcnt(0)
	s_barrier
	s_setprio 1
	s_waitcnt lgkmcnt(0)
	v_mfma_f32_16x16x32_bf16 v[92:95], v[140:143], v[176:179], v[92:95]
	v_mfma_f32_16x16x32_bf16 v[88:91], v[152:155], v[176:179], v[88:91]
	v_mfma_f32_16x16x32_bf16 v[76:79], v[140:143], v[184:187], v[76:79]
	v_mfma_f32_16x16x32_bf16 v[72:75], v[152:155], v[184:187], v[72:75]
	v_mfma_f32_16x16x32_bf16 v[60:63], v[140:143], v[192:195], v[60:63]
	v_mfma_f32_16x16x32_bf16 v[56:59], v[152:155], v[192:195], v[56:59]
	v_mfma_f32_16x16x32_bf16 v[124:127], v[140:143], v[210:213], v[124:127]
	v_mfma_f32_16x16x32_bf16 v[120:123], v[152:155], v[210:213], v[120:123]
	v_mfma_f32_16x16x32_bf16 v[92:95], v[148:151], v[180:183], v[92:95]
	v_mfma_f32_16x16x32_bf16 v[88:91], v[156:159], v[180:183], v[88:91]
	v_mfma_f32_16x16x32_bf16 v[76:79], v[148:151], v[188:191], v[76:79]
	v_mfma_f32_16x16x32_bf16 v[72:75], v[156:159], v[188:191], v[72:75]
	v_mfma_f32_16x16x32_bf16 v[60:63], v[148:151], v[206:209], v[60:63]
	v_mfma_f32_16x16x32_bf16 v[56:59], v[156:159], v[206:209], v[56:59]
	v_mfma_f32_16x16x32_bf16 v[124:127], v[148:151], v[214:217], v[124:127]
	v_mfma_f32_16x16x32_bf16 v[120:123], v[156:159], v[214:217], v[120:123]
	s_setprio 0
	s_setprio 1
	v_mfma_f32_16x16x32_bf16 v[84:87], v[160:163], v[176:179], v[84:87]
	v_mfma_f32_16x16x32_bf16 v[80:83], v[168:171], v[176:179], v[80:83]
	v_mfma_f32_16x16x32_bf16 v[68:71], v[160:163], v[184:187], v[68:71]
	v_mfma_f32_16x16x32_bf16 v[64:67], v[168:171], v[184:187], v[64:67]
	v_mfma_f32_16x16x32_bf16 v[52:55], v[160:163], v[192:195], v[52:55]
	v_mfma_f32_16x16x32_bf16 v[48:51], v[168:171], v[192:195], v[48:51]
	v_mfma_f32_16x16x32_bf16 v[116:119], v[160:163], v[210:213], v[116:119]
	v_mfma_f32_16x16x32_bf16 v[112:115], v[168:171], v[210:213], v[112:115]
	v_mfma_f32_16x16x32_bf16 v[84:87], v[164:167], v[180:183], v[84:87]
	v_mfma_f32_16x16x32_bf16 v[80:83], v[172:175], v[180:183], v[80:83]
	v_mfma_f32_16x16x32_bf16 v[68:71], v[164:167], v[188:191], v[68:71]
	v_mfma_f32_16x16x32_bf16 v[64:67], v[172:175], v[188:191], v[64:67]
	v_mfma_f32_16x16x32_bf16 v[52:55], v[164:167], v[206:209], v[52:55]
	v_mfma_f32_16x16x32_bf16 v[48:51], v[172:175], v[206:209], v[48:51]
	v_mfma_f32_16x16x32_bf16 v[116:119], v[164:167], v[214:217], v[116:119]
	v_mfma_f32_16x16x32_bf16 v[112:115], v[172:175], v[214:217], v[112:115]
	s_setprio 0
	s_barrier
; #define PG8_STAGE(bufoff, gbase, voff) do { _Pragma("unroll") for (int _i = 0; _i < 2; ++_i) \
;         __builtin_amdgcn_global_load_lds((const unsigned*)((const char*)(gbase) + (voff)[_i]), (LAS unsigned*)(lds + (bufoff) + ldsw + _i * 8192), 16, 0, 0); } while (0)
; #define PG8_LDA(dst, b, h) do { _Pragma("unroll") for (int m = 0; m < 4; ++m) _Pragma("unroll") for (int k = 0; k < 2; ++k) dst[m][k] = *(const LAS bf16x8*)(lds + PG8_SA(b, h) + aoff + m * 2048 + k * 1024); } while (0)
; #define PG8_MMA(ai, bj, At, Bt) do { __builtin_amdgcn_s_setprio(1); _Pragma("unroll") for (int m = 0; m < 4; ++m) _Pragma("unroll") for (int n = 0; n < 2; ++n) _Pragma("unroll") for (int k = 0; k < 2; ++k) \
;         acc[ai][bj][m][n] = __builtin_amdgcn_mfma_f32_16x16x32_bf16(Bt[n][k], At[m][k], acc[ai][bj][m][n], 0, 0, 0); __builtin_amdgcn_s_setprio(0); } while (0)
; #define PG8_WAIT_V(n) asm volatile("s_waitcnt vmcnt(" #n ")" ::: "memory")
; #define PG8_WAIT_L(n) asm volatile("s_waitcnt lgkmcnt(" #n ")" ::: "memory")
; #define PG8_BAR __builtin_amdgcn_s_barrier()
; #define PG8_SCHED __builtin_amdgcn_sched_barrier(0)
; template <class Epi, class Sched>
; __device__ __forceinline__ void gemm_phase(LAS unsigned char* lds, const GemmP g, const Sched& S, const Epi& E, int tid) {
;     ...
;             PG8_LDA(At, 1, 1); PG8_STAGE(PG8_SB(1, 0), b3, voffB); PG8_STAGE(PG8_SB(1, 1), b3 + hstepB, voffB); PG8_STAGE(PG8_SA(1, 0), a3, voffA);
;             PG8_WAIT_V(8); PG8_WAIT_L(0); PG8_BAR; PG8_MMA(1, 0, At, B0); PG8_MMA(1, 1, At, B1); PG8_BAR; PG8_SCHED;
;         }
	s_add_i32 s12, s39, s52
	v_lshl_add_u64 v[144:145], v[144:145], 0, s[80:81]
	s_mov_b32 m0, s12
	ds_read_b128 v[176:179], v147 offset:49152
	ds_read_b128 v[180:183], v230 offset:49152
	ds_read_b128 v[184:187], v147 offset:51200
	ds_read_b128 v[188:191], v230 offset:51200
	ds_read_b128 v[192:195], v147 offset:53248
	ds_read_b128 v[206:209], v230 offset:53248
	ds_read_b128 v[210:213], v147 offset:55296
	ds_read_b128 v[214:217], v230 offset:55296
	global_load_lds_dwordx4 v[144:145], off
	s_add_i32 m0, s12, 0x2000
	s_add_u32 s10, s10, 0x40080
	v_lshl_add_u64 v[144:145], v[198:199], 0, s[80:81]
	s_addc_u32 s11, s11, 0
	s_add_i32 s12, s48, s52
	global_load_lds_dwordx4 v[144:145], off
	v_lshl_add_u64 v[144:145], s[10:11], 0, v[130:131]
	s_mov_b32 m0, s12
	s_nop 0
	global_load_lds_dwordx4 v[144:145], off
	v_lshl_add_u64 v[144:145], s[10:11], 0, v[134:135]
	s_add_i32 m0, s12, 0x2000
	s_nop 0
	global_load_lds_dwordx4 v[144:145], off
	v_lshl_add_u64 v[144:145], v[200:201], 0, s[80:81]
	s_mov_b32 m0, s89
	s_nop 0
	global_load_lds_dwordx4 v[144:145], off
	v_lshl_add_u64 v[144:145], v[220:221], 0, s[80:81]
	s_mov_b32 m0, s64
	s_nop 0
	global_load_lds_dwordx4 v[144:145], off
	s_waitcnt vmcnt(8)
	s_waitcnt lgkmcnt(0)
	s_barrier
	s_setprio 1
	s_waitcnt lgkmcnt(0)
	v_mfma_f32_16x16x32_bf16 v[44:47], v[140:143], v[176:179], v[44:47]
	v_mfma_f32_16x16x32_bf16 v[40:43], v[152:155], v[176:179], v[40:43]
	v_mfma_f32_16x16x32_bf16 v[28:31], v[140:143], v[184:187], v[28:31]
	v_mfma_f32_16x16x32_bf16 v[24:27], v[152:155], v[184:187], v[24:27]
	v_mfma_f32_16x16x32_bf16 v[12:15], v[140:143], v[192:195], v[12:15]
	v_mfma_f32_16x16x32_bf16 v[8:11], v[152:155], v[192:195], v[8:11]
	v_mfma_f32_16x16x32_bf16 v[108:111], v[140:143], v[210:213], v[108:111]
	v_mfma_f32_16x16x32_bf16 v[104:107], v[152:155], v[210:213], v[104:107]
	v_mfma_f32_16x16x32_bf16 v[44:47], v[148:151], v[180:183], v[44:47]
	v_mfma_f32_16x16x32_bf16 v[40:43], v[156:159], v[180:183], v[40:43]
	v_mfma_f32_16x16x32_bf16 v[28:31], v[148:151], v[188:191], v[28:31]
	v_mfma_f32_16x16x32_bf16 v[24:27], v[156:159], v[188:191], v[24:27]
	v_mfma_f32_16x16x32_bf16 v[12:15], v[148:151], v[206:209], v[12:15]
	v_mfma_f32_16x16x32_bf16 v[8:11], v[156:159], v[206:209], v[8:11]
	v_mfma_f32_16x16x32_bf16 v[108:111], v[148:151], v[214:217], v[108:111]
	v_mfma_f32_16x16x32_bf16 v[104:107], v[156:159], v[214:217], v[104:107]
	s_setprio 0
	s_setprio 1
	v_mfma_f32_16x16x32_bf16 v[36:39], v[160:163], v[176:179], v[36:39]
	v_mfma_f32_16x16x32_bf16 v[32:35], v[168:171], v[176:179], v[32:35]
	v_mfma_f32_16x16x32_bf16 v[20:23], v[160:163], v[184:187], v[20:23]
	v_mfma_f32_16x16x32_bf16 v[16:19], v[168:171], v[184:187], v[16:19]
	v_mfma_f32_16x16x32_bf16 v[4:7], v[160:163], v[192:195], v[4:7]
	v_mfma_f32_16x16x32_bf16 v[0:3], v[168:171], v[192:195], v[0:3]
	v_mfma_f32_16x16x32_bf16 v[100:103], v[160:163], v[210:213], v[100:103]
	v_mfma_f32_16x16x32_bf16 v[96:99], v[168:171], v[210:213], v[96:99]
	v_mfma_f32_16x16x32_bf16 v[36:39], v[164:167], v[180:183], v[36:39]
	v_mfma_f32_16x16x32_bf16 v[32:35], v[172:175], v[180:183], v[32:35]
	v_mfma_f32_16x16x32_bf16 v[20:23], v[164:167], v[188:191], v[20:23]
	v_mfma_f32_16x16x32_bf16 v[16:19], v[172:175], v[188:191], v[16:19]
	v_mfma_f32_16x16x32_bf16 v[4:7], v[164:167], v[206:209], v[4:7]
	v_mfma_f32_16x16x32_bf16 v[0:3], v[172:175], v[206:209], v[0:3]
	v_mfma_f32_16x16x32_bf16 v[100:103], v[164:167], v[214:217], v[100:103]
	v_mfma_f32_16x16x32_bf16 v[96:99], v[172:175], v[214:217], v[96:99]
	s_setprio 0
	s_barrier
	s_add_i32 s38, s38, 2
	s_add_u32 s14, s14, 0x100
	s_addc_u32 s15, s15, 0
	s_add_u32 s6, s6, 0x100
	s_addc_u32 s7, s7, 0
	s_cmp_gt_u32 s38, 13
	s_cbranch_scc0 .LBB0_1390
	s_and_b64 vcc, exec, s[2:3]
	s_cbranch_vccz .LBB0_1393
	s_barrier
